# v5: + pipelined out-proj K-loop, cross-half max exchange only on rescale
# speedup vs baseline: 1.0289x; 1.0078x over previous
.LBB0_18:
.LBB0_19:
	v_readfirstlane_b32 s27, v121
	s_mul_i32 s36, s35, 0xc000
	s_add_i32 s8, s35, -1
	s_cmp_eq_u32 s35, 0
	s_cselect_b32 s8, 2, s8
	s_mul_i32 s8, s8, 0xc000
	s_add_i32 s26, s8, s27
	v_add3_u32 v250, s36, v142, v141
	v_add3_u32 v251, s36, v123, v141
	ds_read_b128 v[82:85], v250 offset:0
	ds_read_b128 v[66:69], v251 offset:32768
	ds_read_b128 v[70:73], v251 offset:34816
	ds_read_b128 v[214:217], v250 offset:2048
	ds_read_b128 v[218:221], v250 offset:4096
	ds_read_b128 v[222:225], v250 offset:6144
	ds_read_b128 v[234:237], v250 offset:8192
	ds_read_b128 v[238:241], v250 offset:10240
.Lgo_loop:
	s_waitcnt lgkmcnt(5)
	v_mfma_f32_16x16x32_bf16 v[62:65], v[82:85], v[66:69], v[62:65]
	v_mfma_f32_16x16x32_bf16 v[58:61], v[82:85], v[70:73], v[58:61]
	ds_read_b128 v[242:245], v250 offset:12288
	s_cmp_gt_u32 s11, 13
	s_cbranch_scc1 .Lgo_nodma0
	v_lshl_add_u64 v[150:151], v[134:135], 0, s[20:21]
	s_add_i32 m0, s26, 0x0
	s_nop 0
	global_load_lds_dwordx4 v[150:151], off
.Lgo_nodma0:
	s_waitcnt lgkmcnt(5)
	v_mfma_f32_16x16x32_bf16 v[54:57], v[214:217], v[66:69], v[54:57]
	v_mfma_f32_16x16x32_bf16 v[50:53], v[214:217], v[70:73], v[50:53]
	ds_read_b128 v[246:249], v250 offset:14336
	s_cmp_gt_u32 s11, 13
	s_cbranch_scc1 .Lgo_nodma1
	v_lshl_add_u64 v[150:151], v[132:133], 0, s[20:21]
	s_add_i32 m0, s26, 0x8000
	s_nop 0
	global_load_lds_dwordx4 v[150:151], off
.Lgo_nodma1:
	s_waitcnt lgkmcnt(5)
	v_mfma_f32_16x16x32_bf16 v[46:49], v[218:221], v[66:69], v[46:49]
	v_mfma_f32_16x16x32_bf16 v[42:45], v[218:221], v[70:73], v[42:45]
	ds_read_b128 v[82:85], v250 offset:1024
	ds_read_b128 v[74:77], v251 offset:33792
	s_cmp_gt_u32 s11, 13
	s_cbranch_scc1 .Lgo_nodma2
	v_lshl_add_u64 v[150:151], v[130:131], 0, s[20:21]
	s_add_i32 m0, s26, 0x2000
	s_nop 0
	global_load_lds_dwordx4 v[150:151], off
.Lgo_nodma2:
	s_waitcnt lgkmcnt(6)
	v_mfma_f32_16x16x32_bf16 v[38:41], v[222:225], v[66:69], v[38:41]
	v_mfma_f32_16x16x32_bf16 v[34:37], v[222:225], v[70:73], v[34:37]
	ds_read_b128 v[214:217], v250 offset:3072
	ds_read_b128 v[78:81], v251 offset:35840
	s_cmp_gt_u32 s11, 13
	s_cbranch_scc1 .Lgo_nodma3
	v_lshl_add_u64 v[150:151], v[128:129], 0, s[20:21]
	s_add_i32 m0, s26, 0xa000
	s_nop 0
	global_load_lds_dwordx4 v[150:151], off
.Lgo_nodma3:
	s_waitcnt lgkmcnt(7)
	v_mfma_f32_16x16x32_bf16 v[30:33], v[234:237], v[66:69], v[30:33]
	v_mfma_f32_16x16x32_bf16 v[26:29], v[234:237], v[70:73], v[26:29]
	ds_read_b128 v[218:221], v250 offset:5120
	s_cmp_gt_u32 s11, 13
	s_cbranch_scc1 .Lgo_nodma4
	v_lshl_add_u64 v[150:151], v[126:127], 0, s[20:21]
	s_add_i32 m0, s26, 0x4000
	s_nop 0
	global_load_lds_dwordx4 v[150:151], off
.Lgo_nodma4:
	s_waitcnt lgkmcnt(7)
	v_mfma_f32_16x16x32_bf16 v[22:25], v[238:241], v[66:69], v[22:25]
	v_mfma_f32_16x16x32_bf16 v[18:21], v[238:241], v[70:73], v[18:21]
	ds_read_b128 v[222:225], v250 offset:7168
	s_cmp_gt_u32 s11, 13
	s_cbranch_scc1 .Lgo_nodma5
	v_lshl_add_u64 v[150:151], v[124:125], 0, s[20:21]
	s_add_i32 m0, s26, 0x6000
	s_nop 0
	global_load_lds_dwordx4 v[150:151], off
.Lgo_nodma5:
	s_waitcnt lgkmcnt(7)
	v_mfma_f32_16x16x32_bf16 v[14:17], v[242:245], v[66:69], v[14:17]
	v_mfma_f32_16x16x32_bf16 v[10:13], v[242:245], v[70:73], v[10:13]
	ds_read_b128 v[234:237], v250 offset:9216
	s_waitcnt lgkmcnt(7)
	v_mfma_f32_16x16x32_bf16 v[6:9], v[246:249], v[66:69], v[6:9]
	v_mfma_f32_16x16x32_bf16 v[2:5], v[246:249], v[70:73], v[2:5]
	ds_read_b128 v[238:241], v250 offset:11264
	s_waitcnt lgkmcnt(4)
	v_mfma_f32_16x16x32_bf16 v[62:65], v[82:85], v[74:77], v[62:65]
	v_mfma_f32_16x16x32_bf16 v[58:61], v[82:85], v[78:81], v[58:61]
	ds_read_b128 v[242:245], v250 offset:13312
	v_mfma_f32_16x16x32_bf16 v[54:57], v[214:217], v[74:77], v[54:57]
	v_mfma_f32_16x16x32_bf16 v[50:53], v[214:217], v[78:81], v[50:53]
	ds_read_b128 v[246:249], v250 offset:15360
	s_waitcnt lgkmcnt(5)
	v_mfma_f32_16x16x32_bf16 v[46:49], v[218:221], v[74:77], v[46:49]
	v_mfma_f32_16x16x32_bf16 v[42:45], v[218:221], v[78:81], v[42:45]
	s_waitcnt lgkmcnt(4)
	v_mfma_f32_16x16x32_bf16 v[38:41], v[222:225], v[74:77], v[38:41]
	v_mfma_f32_16x16x32_bf16 v[34:37], v[222:225], v[78:81], v[34:37]
	s_waitcnt lgkmcnt(3)
	v_mfma_f32_16x16x32_bf16 v[30:33], v[234:237], v[74:77], v[30:33]
	v_mfma_f32_16x16x32_bf16 v[26:29], v[234:237], v[78:81], v[26:29]
	s_waitcnt lgkmcnt(2)
	v_mfma_f32_16x16x32_bf16 v[22:25], v[238:241], v[74:77], v[22:25]
	v_mfma_f32_16x16x32_bf16 v[18:21], v[238:241], v[78:81], v[18:21]
	s_waitcnt lgkmcnt(1)
	v_mfma_f32_16x16x32_bf16 v[14:17], v[242:245], v[74:77], v[14:17]
	v_mfma_f32_16x16x32_bf16 v[10:13], v[242:245], v[78:81], v[10:13]
	s_waitcnt lgkmcnt(0)
	s_cmp_gt_u32 s11, 13
	s_cbranch_scc1 .Lgo_w0
	s_waitcnt vmcnt(6)
	s_branch .Lgo_wd

.Lgo_wd:
	s_barrier
	s_add_i32 s11, s11, 1
	s_add_u32 s20, s20, 0x80
	s_addc_u32 s21, s21, 0
	s_add_i32 s9, s35, 1
	s_cmp_lg_u32 s35, 2
	s_cselect_b32 s35, s9, 0
	s_cmpk_eq_i32 s20, 0x800
	s_cbranch_scc1 .Lgo_tail
	s_mul_i32 s36, s35, 0xc000
	s_add_i32 s8, s35, -1
	s_cmp_eq_u32 s35, 0
	s_cselect_b32 s8, 2, s8
	s_mul_i32 s8, s8, 0xc000
	s_add_i32 s26, s8, s27
	v_add3_u32 v250, s36, v142, v141
	v_add3_u32 v251, s36, v123, v141
	ds_read_b128 v[82:85], v250 offset:0
	ds_read_b128 v[66:69], v251 offset:32768
	ds_read_b128 v[70:73], v251 offset:34816
	ds_read_b128 v[214:217], v250 offset:2048
	ds_read_b128 v[218:221], v250 offset:4096
	ds_read_b128 v[222:225], v250 offset:6144
	ds_read_b128 v[234:237], v250 offset:8192
	ds_read_b128 v[238:241], v250 offset:10240
	v_mfma_f32_16x16x32_bf16 v[6:9], v[246:249], v[74:77], v[6:9]
	v_mfma_f32_16x16x32_bf16 v[2:5], v[246:249], v[78:81], v[2:5]
	s_branch .Lgo_loop
.Lgo_tail:
	v_mfma_f32_16x16x32_bf16 v[6:9], v[246:249], v[74:77], v[6:9]
	v_mfma_f32_16x16x32_bf16 v[2:5], v[246:249], v[78:81], v[2:5]

.LBB0_119:
	ds_read_b128 v[2:5], v218
	ds_read_b128 v[6:9], v218 offset:32
	s_cmpk_lg_i32 s3, 0xffc3
	s_waitcnt lgkmcnt(1)
	v_mfma_f32_32x32x16_bf16 v[112:127], v[2:5], v[144:147], v[80:95]
	s_waitcnt lgkmcnt(0)
	v_mfma_f32_32x32x16_bf16 v[112:127], v[6:9], v[148:151], v[112:127]
	ds_read_b128 v[2:5], v218 offset:64
	ds_read_b128 v[6:9], v218 offset:96
	s_waitcnt lgkmcnt(1)
	v_mfma_f32_32x32x16_bf16 v[112:127], v[2:5], v[152:155], v[112:127]
	s_waitcnt lgkmcnt(0)
	v_mfma_f32_32x32x16_bf16 v[112:127], v[6:9], v[156:159], v[112:127]
	ds_read_b128 v[2:5], v218 offset:4608
	ds_read_b128 v[6:9], v218 offset:4640
	s_waitcnt lgkmcnt(1)
	v_mfma_f32_32x32x16_bf16 v[128:143], v[2:5], v[144:147], v[80:95]
	s_nop 7
	v_max_f32_e32 v0, v113, v113
	v_max_f32_e32 v11, v112, v112
	v_max_f32_e32 v0, v11, v0
	v_max3_f32 v0, v0, v114, v115
	v_max3_f32 v0, v0, v116, v117
	v_max3_f32 v0, v0, v118, v119
	v_max3_f32 v0, v0, v120, v121
	s_waitcnt lgkmcnt(0)
	v_mfma_f32_32x32x16_bf16 v[128:143], v[6:9], v[148:151], v[128:143]
	ds_read_b128 v[2:5], v218 offset:4672
	ds_read_b128 v[6:9], v218 offset:4704
	v_max3_f32 v0, v0, v122, v123
	v_max3_f32 v0, v0, v124, v125
	v_max3_f32 v0, v0, v126, v127
	s_waitcnt lgkmcnt(1)
	v_mfma_f32_32x32x16_bf16 v[128:143], v[2:5], v[152:155], v[128:143]
	v_and_b32_e32 v3, 64, v228
	v_xor_b32_e32 v2, 32, v228
	v_add_u32_e32 v3, 64, v3
	v_cmp_lt_i32_e32 vcc, v2, v3
	s_nop 1
	v_cndmask_b32_e32 v2, v228, v2, vcc
	s_waitcnt lgkmcnt(0)
	v_mfma_f32_32x32x16_bf16 v[128:143], v[6:9], v[156:159], v[128:143]
	v_lshlrev_b32_e32 v212, 2, v2
	s_nop 10
	v_max3_f32 v0, v0, v128, v129
	v_max3_f32 v0, v0, v130, v131
	v_max3_f32 v0, v0, v132, v133
	v_max3_f32 v0, v0, v134, v135
	v_max3_f32 v0, v0, v136, v137
	v_max3_f32 v0, v0, v138, v139
	v_max3_f32 v0, v0, v140, v141
	v_max3_f32 v0, v0, v142, v143
	s_cbranch_scc0 .Ld_first
	v_cmp_lt_f32_e32 vcc, s88, v0
	s_mov_b64 s[6:7], 0
	s_mov_b64 s[10:11], 0
	s_cbranch_vccz .LBB0_127
	ds_bpermute_b32 v2, v212, v0
	s_waitcnt lgkmcnt(0)
	v_max_f32_e32 v2, v2, v2
	v_max_f32_e32 v0, v0, v2
	v_max_f32_e32 v0, 0, v0
	s_branch .Ld_resc
.Ld_first:
	ds_bpermute_b32 v2, v212, v0
	s_waitcnt lgkmcnt(0)
	v_max_f32_e32 v2, v2, v2
	v_max_f32_e32 v0, v0, v2
.Ld_resc:
	v_exp_f32_e64 v2, -v0
	v_add_f32_e32 v10, v10, v0
	v_xor_b32_e32 v96, 0x80000000, v10
	v_pk_add_f32 v[112:113], v[112:113], v[0:1] op_sel_hi:[1,0] neg_lo:[0,1] neg_hi:[0,1]
	v_pk_add_f32 v[114:115], v[114:115], v[0:1] op_sel_hi:[1,0] neg_lo:[0,1] neg_hi:[0,1]
	v_pk_add_f32 v[116:117], v[116:117], v[0:1] op_sel_hi:[1,0] neg_lo:[0,1] neg_hi:[0,1]
	v_pk_add_f32 v[118:119], v[118:119], v[0:1] op_sel_hi:[1,0] neg_lo:[0,1] neg_hi:[0,1]
	v_pk_add_f32 v[120:121], v[120:121], v[0:1] op_sel_hi:[1,0] neg_lo:[0,1] neg_hi:[0,1]
	v_pk_add_f32 v[122:123], v[122:123], v[0:1] op_sel_hi:[1,0] neg_lo:[0,1] neg_hi:[0,1]
	v_pk_add_f32 v[124:125], v[124:125], v[0:1] op_sel_hi:[1,0] neg_lo:[0,1] neg_hi:[0,1]
	v_pk_add_f32 v[126:127], v[126:127], v[0:1] op_sel_hi:[1,0] neg_lo:[0,1] neg_hi:[0,1]
	v_pk_add_f32 v[128:129], v[128:129], v[0:1] op_sel_hi:[1,0] neg_lo:[0,1] neg_hi:[0,1]
	v_pk_add_f32 v[130:131], v[130:131], v[0:1] op_sel_hi:[1,0] neg_lo:[0,1] neg_hi:[0,1]
	v_pk_add_f32 v[132:133], v[132:133], v[0:1] op_sel_hi:[1,0] neg_lo:[0,1] neg_hi:[0,1]
	v_pk_add_f32 v[134:135], v[134:135], v[0:1] op_sel_hi:[1,0] neg_lo:[0,1] neg_hi:[0,1]
	v_pk_add_f32 v[136:137], v[136:137], v[0:1] op_sel_hi:[1,0] neg_lo:[0,1] neg_hi:[0,1]
	v_pk_add_f32 v[138:139], v[138:139], v[0:1] op_sel_hi:[1,0] neg_lo:[0,1] neg_hi:[0,1]
	v_pk_add_f32 v[140:141], v[140:141], v[0:1] op_sel_hi:[1,0] neg_lo:[0,1] neg_hi:[0,1]
	v_pk_add_f32 v[142:143], v[142:143], v[0:1] op_sel_hi:[1,0] neg_lo:[0,1] neg_hi:[0,1]
	v_mul_f32_e32 v223, v223, v2
	v_pk_mul_f32 v[78:79], v[78:79], v[2:3] op_sel_hi:[1,0]
	v_pk_mul_f32 v[76:77], v[76:77], v[2:3] op_sel_hi:[1,0]
	v_pk_mul_f32 v[74:75], v[74:75], v[2:3] op_sel_hi:[1,0]
	v_pk_mul_f32 v[72:73], v[72:73], v[2:3] op_sel_hi:[1,0]
	v_pk_mul_f32 v[70:71], v[70:71], v[2:3] op_sel_hi:[1,0]
	v_pk_mul_f32 v[68:69], v[68:69], v[2:3] op_sel_hi:[1,0]
	v_pk_mul_f32 v[66:67], v[66:67], v[2:3] op_sel_hi:[1,0]
	v_pk_mul_f32 v[64:65], v[64:65], v[2:3] op_sel_hi:[1,0]
	v_pk_mul_f32 v[62:63], v[62:63], v[2:3] op_sel_hi:[1,0]
	v_pk_mul_f32 v[60:61], v[60:61], v[2:3] op_sel_hi:[1,0]
	v_pk_mul_f32 v[58:59], v[58:59], v[2:3] op_sel_hi:[1,0]
	v_pk_mul_f32 v[56:57], v[56:57], v[2:3] op_sel_hi:[1,0]
	v_pk_mul_f32 v[54:55], v[54:55], v[2:3] op_sel_hi:[1,0]
	v_pk_mul_f32 v[52:53], v[52:53], v[2:3] op_sel_hi:[1,0]
	v_pk_mul_f32 v[50:51], v[50:51], v[2:3] op_sel_hi:[1,0]
	v_pk_mul_f32 v[48:49], v[48:49], v[2:3] op_sel_hi:[1,0]
	v_pk_mul_f32 v[46:47], v[46:47], v[2:3] op_sel_hi:[1,0]
	v_pk_mul_f32 v[44:45], v[44:45], v[2:3] op_sel_hi:[1,0]
	v_pk_mul_f32 v[42:43], v[42:43], v[2:3] op_sel_hi:[1,0]
	v_pk_mul_f32 v[40:41], v[40:41], v[2:3] op_sel_hi:[1,0]
	v_pk_mul_f32 v[38:39], v[38:39], v[2:3] op_sel_hi:[1,0]
	v_pk_mul_f32 v[36:37], v[36:37], v[2:3] op_sel_hi:[1,0]
	v_pk_mul_f32 v[34:35], v[34:35], v[2:3] op_sel_hi:[1,0]
	v_pk_mul_f32 v[32:33], v[32:33], v[2:3] op_sel_hi:[1,0]
	v_pk_mul_f32 v[30:31], v[30:31], v[2:3] op_sel_hi:[1,0]
	v_pk_mul_f32 v[28:29], v[28:29], v[2:3] op_sel_hi:[1,0]
	v_pk_mul_f32 v[26:27], v[26:27], v[2:3] op_sel_hi:[1,0]
	v_pk_mul_f32 v[24:25], v[24:25], v[2:3] op_sel_hi:[1,0]
	v_pk_mul_f32 v[22:23], v[22:23], v[2:3] op_sel_hi:[1,0]
	v_pk_mul_f32 v[20:21], v[20:21], v[2:3] op_sel_hi:[1,0]
	v_pk_mul_f32 v[18:19], v[18:19], v[2:3] op_sel_hi:[1,0]
	v_pk_mul_f32 v[16:17], v[16:17], v[2:3] op_sel_hi:[1,0]
	v_mov_b32_e32 v97, v96
	v_mov_b32_e32 v98, v96
	v_mov_b32_e32 v99, v96
	v_mov_b32_e32 v100, v96
	v_mov_b32_e32 v101, v96
	v_mov_b32_e32 v102, v96
	v_mov_b32_e32 v103, v96
	v_mov_b32_e32 v104, v96
	v_mov_b32_e32 v105, v96
	v_mov_b32_e32 v106, v96
	v_mov_b32_e32 v107, v96
	v_mov_b32_e32 v108, v96
	v_mov_b32_e32 v109, v96
	v_mov_b32_e32 v110, v96
	v_mov_b32_e32 v111, v96
	v_mov_b32_e32 v80, v96
	v_mov_b32_e32 v81, v96
	v_mov_b32_e32 v82, v96
	v_mov_b32_e32 v83, v96
	v_mov_b32_e32 v84, v96
	v_mov_b32_e32 v85, v96
	v_mov_b32_e32 v86, v96
	v_mov_b32_e32 v87, v96
	v_mov_b32_e32 v88, v96
	v_mov_b32_e32 v89, v96
	v_mov_b32_e32 v90, v96
	v_mov_b32_e32 v91, v96
	v_mov_b32_e32 v92, v96
	v_mov_b32_e32 v93, v96
	v_mov_b32_e32 v94, v96
	v_mov_b32_e32 v95, v96
	s_branch .LBB0_128

.LBB0_227:
	v_max_f32_e32 v0, v147, v147
	v_max_f32_e32 v50, v146, v146
	v_max_f32_e32 v0, v50, v0
	v_max3_f32 v0, v0, v148, v149
	v_max3_f32 v0, v0, v150, v151
	v_max3_f32 v0, v0, v152, v153
	v_max3_f32 v0, v0, v154, v155
	v_max3_f32 v0, v0, v156, v157
	v_max3_f32 v0, v0, v158, v159
	v_max3_f32 v0, v0, v160, v161
	v_max3_f32 v0, v0, v162, v163
	v_max3_f32 v0, v0, v164, v165
	v_max3_f32 v0, v0, v166, v167
	v_max3_f32 v0, v0, v168, v169
	v_and_b32_e32 v51, 64, v228
	v_max3_f32 v0, v0, v170, v171
	v_xor_b32_e32 v50, 32, v228
	v_add_u32_e32 v51, 64, v51
	v_max3_f32 v0, v0, v172, v173
	v_cmp_lt_i32_e32 vcc, v50, v51
	v_max3_f32 v0, v0, v174, v175
	v_max3_f32 v0, v0, v176, v177
	v_cndmask_b32_e32 v50, v228, v50, vcc
	v_lshlrev_b32_e32 v50, 2, v50
	s_cmp_lg_u32 s85, 0
	s_cbranch_scc0 .Ln_first
	v_cmp_lt_f32_e32 vcc, s88, v0
	s_mov_b64 s[76:77], 0
	s_mov_b64 s[6:7], 0
	s_cbranch_vccz .LBB0_148
	ds_bpermute_b32 v50, v50, v0
	s_waitcnt lgkmcnt(0)
	v_max_f32_e32 v50, v50, v50
	v_max_f32_e32 v0, v0, v50
	v_max_f32_e32 v0, 0, v0
	s_branch .Ln_resc
.Ln_first:
	ds_bpermute_b32 v50, v50, v0
	s_waitcnt lgkmcnt(0)
	v_max_f32_e32 v50, v50, v50
	v_max_f32_e32 v0, v0, v50
.Ln_resc:
	v_exp_f32_e64 v36, -v0
	v_add_f32_e32 v194, v194, v0
	v_xor_b32_e32 v34, 0x80000000, v194
	v_pk_add_f32 v[146:147], v[146:147], v[0:1] op_sel_hi:[1,0] neg_lo:[0,1] neg_hi:[0,1]
	v_pk_add_f32 v[148:149], v[148:149], v[0:1] op_sel_hi:[1,0] neg_lo:[0,1] neg_hi:[0,1]
	v_pk_add_f32 v[150:151], v[150:151], v[0:1] op_sel_hi:[1,0] neg_lo:[0,1] neg_hi:[0,1]
	v_pk_add_f32 v[152:153], v[152:153], v[0:1] op_sel_hi:[1,0] neg_lo:[0,1] neg_hi:[0,1]
	v_pk_add_f32 v[154:155], v[154:155], v[0:1] op_sel_hi:[1,0] neg_lo:[0,1] neg_hi:[0,1]
	v_pk_add_f32 v[156:157], v[156:157], v[0:1] op_sel_hi:[1,0] neg_lo:[0,1] neg_hi:[0,1]
	v_pk_add_f32 v[158:159], v[158:159], v[0:1] op_sel_hi:[1,0] neg_lo:[0,1] neg_hi:[0,1]
	v_pk_add_f32 v[160:161], v[160:161], v[0:1] op_sel_hi:[1,0] neg_lo:[0,1] neg_hi:[0,1]
	v_pk_add_f32 v[162:163], v[162:163], v[0:1] op_sel_hi:[1,0] neg_lo:[0,1] neg_hi:[0,1]
	v_pk_add_f32 v[164:165], v[164:165], v[0:1] op_sel_hi:[1,0] neg_lo:[0,1] neg_hi:[0,1]
	v_pk_add_f32 v[166:167], v[166:167], v[0:1] op_sel_hi:[1,0] neg_lo:[0,1] neg_hi:[0,1]
	v_pk_add_f32 v[168:169], v[168:169], v[0:1] op_sel_hi:[1,0] neg_lo:[0,1] neg_hi:[0,1]
	v_pk_add_f32 v[170:171], v[170:171], v[0:1] op_sel_hi:[1,0] neg_lo:[0,1] neg_hi:[0,1]
	v_pk_add_f32 v[172:173], v[172:173], v[0:1] op_sel_hi:[1,0] neg_lo:[0,1] neg_hi:[0,1]
	v_pk_add_f32 v[174:175], v[174:175], v[0:1] op_sel_hi:[1,0] neg_lo:[0,1] neg_hi:[0,1]
	v_pk_add_f32 v[176:177], v[176:177], v[0:1] op_sel_hi:[1,0] neg_lo:[0,1] neg_hi:[0,1]
	v_pk_mul_f32 v[16:17], v[16:17], v[36:37] op_sel_hi:[1,0]
	v_pk_mul_f32 v[14:15], v[14:15], v[36:37] op_sel_hi:[1,0]
	v_pk_mul_f32 v[12:13], v[12:13], v[36:37] op_sel_hi:[1,0]
	v_pk_mul_f32 v[10:11], v[10:11], v[36:37] op_sel_hi:[1,0]
	v_pk_mul_f32 v[8:9], v[8:9], v[36:37] op_sel_hi:[1,0]
	v_pk_mul_f32 v[6:7], v[6:7], v[36:37] op_sel_hi:[1,0]
	v_pk_mul_f32 v[4:5], v[4:5], v[36:37] op_sel_hi:[1,0]
	v_pk_mul_f32 v[2:3], v[2:3], v[36:37] op_sel_hi:[1,0]
	v_pk_mul_f32 v[32:33], v[32:33], v[36:37] op_sel_hi:[1,0]
	v_pk_mul_f32 v[30:31], v[30:31], v[36:37] op_sel_hi:[1,0]
	v_pk_mul_f32 v[28:29], v[28:29], v[36:37] op_sel_hi:[1,0]
	v_pk_mul_f32 v[26:27], v[26:27], v[36:37] op_sel_hi:[1,0]
	v_pk_mul_f32 v[24:25], v[24:25], v[36:37] op_sel_hi:[1,0]
	v_pk_mul_f32 v[22:23], v[22:23], v[36:37] op_sel_hi:[1,0]
	v_pk_mul_f32 v[20:21], v[20:21], v[36:37] op_sel_hi:[1,0]
	v_pk_mul_f32 v[18:19], v[18:19], v[36:37] op_sel_hi:[1,0]
	v_mul_f32_e32 v191, v191, v36
	v_mov_b32_e32 v35, v34
	v_mov_b32_e32 v36, v34
	v_mov_b32_e32 v37, v34
	v_mov_b32_e32 v38, v34
	v_mov_b32_e32 v39, v34
	v_mov_b32_e32 v40, v34
	v_mov_b32_e32 v41, v34
	v_mov_b32_e32 v42, v34
	v_mov_b32_e32 v43, v34
	v_mov_b32_e32 v44, v34
	v_mov_b32_e32 v45, v34
	v_mov_b32_e32 v46, v34
	v_mov_b32_e32 v47, v34
	v_mov_b32_e32 v48, v34
	v_mov_b32_e32 v49, v34
	s_branch .LBB0_148
